# attention loop: 48 canonicalising self-max (v_max x,x) folded into their consuming max (instruction selection)
# speedup vs baseline: 1.0097x; 1.0009x over previous
.LBB0_414:
	s_add_u32 s29, s90, s4
	s_addc_u32 s30, s91, s5
	s_lshl_b64 s[4:5], s[6:7], vcc_lo
	s_add_u32 s4, s29, s4
	s_addc_u32 s5, s30, s5
	s_waitcnt vmcnt(16)
	v_lshl_add_u64 v[64:65], v[16:17], 1, s[4:5]
	v_lshl_add_u64 v[16:17], v[18:19], 0, v[68:69]
	s_movk_i32 s29, 0x300
	v_mad_u64_u32 v[24:25], s[4:5], v16, s29, v[86:87]
	v_mov_b32_e32 v16, v25
	v_mul_u32_u24_e32 v66, s28, v68
	v_mad_u64_u32 v[26:27], s[4:5], v17, s29, v[16:17]
	v_lshlrev_b32_e32 v192, 1, v66
	v_mov_b32_e32 v25, v26
	v_lshl_add_u64 v[64:65], v[64:65], 0, v[192:193]
	v_mov_b32_e32 v85, v193
	global_load_dwordx4 v[16:19], v[24:25], off
	global_load_dwordx4 v[20:23], v[24:25], off offset:64
	v_add_co_u32_e32 v24, vcc, s93, v24
	v_lshl_add_u64 v[64:65], v[64:65], 0, v[84:85]
	s_lshl_b32 s78, s28, 5
	v_addc_co_u32_e32 v25, vcc, 0, v26, vcc
	v_lshl_add_u64 v[66:67], v[64:65], 0, s[78:79]
	global_load_dwordx4 v[28:31], v[24:25], off
	s_nop 0
	global_load_dwordx4 v[24:27], v[24:25], off offset:64
	s_nop 0
	global_load_dwordx2 v[134:135], v[64:65], off
	global_load_dwordx2 v[136:137], v[64:65], off offset:32
	global_load_dwordx2 v[130:131], v[66:67], off
	global_load_dwordx2 v[132:133], v[66:67], off offset:32
	v_lshl_add_u64 v[64:65], v[66:67], 0, s[78:79]
	v_lshl_add_u64 v[66:67], v[64:65], 0, s[78:79]
	global_load_dwordx2 v[126:127], v[64:65], off
	global_load_dwordx2 v[128:129], v[64:65], off offset:32
	global_load_dwordx2 v[122:123], v[66:67], off
	global_load_dwordx2 v[124:125], v[66:67], off offset:32
	s_cmp_ge_i32 s71, s94
	s_mov_b64 s[28:29], -1
	s_cbranch_scc0 .LBB0_416
	s_waitcnt vmcnt(12)
	v_mfma_f32_16x16x32_bf16 a[0:3], v[146:149], v[0:3], 0
	v_cmp_lt_i32_e32 vcc, v212, v210
	s_mov_b32 s4, 0x7060302
	s_mov_b64 s[28:29], 0
	v_mfma_f32_16x16x32_bf16 a[0:3], v[142:145], v[4:7], a[0:3]
	v_mfma_f32_16x16x32_bf16 a[8:11], v[146:149], v[8:11], 0
	v_mfma_f32_16x16x32_bf16 a[12:15], v[150:153], v[8:11], 0
	s_nop 5
	s_nop 3
	v_accvgpr_read_b32 v64, a0
	v_accvgpr_read_b32 v65, a1
	v_accvgpr_read_b32 v66, a2
	v_accvgpr_read_b32 v67, a3
	v_mfma_f32_16x16x32_bf16 a[0:3], v[150:153], v[0:3], 0


	v_max_f32_e32 v85, v64, v65
	v_mfma_f32_16x16x32_bf16 a[0:3], v[138:141], v[4:7], a[0:3]


	v_max_f32_e32 v90, v66, v67
	v_mfma_f32_16x16x32_bf16 a[8:11], v[142:145], v[12:15], a[8:11]
	v_mfma_f32_16x16x32_bf16 a[12:15], v[138:141], v[12:15], a[12:15]
	s_nop 2
	s_nop 3
	v_accvgpr_read_b32 v154, a2
	v_accvgpr_read_b32 v155, a3


	v_accvgpr_read_b32 v91, a0
	v_accvgpr_read_b32 v105, a1
	v_max_f32_e32 v103, v154, v155
	v_max3_f32 v103, v91, v105, v103
	v_max3_f32 v85, v85, v90, v103
	v_cndmask_b32_e32 v90, v209, v212, vcc
	v_lshlrev_b32_e32 v90, 2, v90
	ds_bpermute_b32 v103, v90, v85
	v_cmp_lt_i32_e32 vcc, v211, v210
	v_accvgpr_read_b32 v165, a11
	v_accvgpr_read_b32 v173, a15
	v_accvgpr_read_b32 v167, a12
	s_waitcnt lgkmcnt(0)
	v_max_f32_e32 v103, v103, v103
	v_max_f32_e32 v85, v85, v103
	v_cndmask_b32_e32 v103, v209, v211, vcc
	v_lshlrev_b32_e32 v159, 2, v103
	ds_bpermute_b32 v103, v159, v85
	v_accvgpr_read_b32 v169, a13
	s_waitcnt lgkmcnt(0)
	v_max3_f32 v103, v102, v85, v103
	v_sub_f32_e32 v64, v64, v103
	v_mul_f32_e32 v64, 0x3fb8aa3b, v64
	v_exp_f32_e32 v158, v64
	v_sub_f32_e32 v64, v65, v103
	v_mul_f32_e32 v64, 0x3fb8aa3b, v64
	v_exp_f32_e32 v160, v64
	v_sub_f32_e32 v64, v66, v103
	v_mul_f32_e32 v64, 0x3fb8aa3b, v64
	v_exp_f32_e32 v162, v64
	v_sub_f32_e32 v64, v67, v103
	v_mul_f32_e32 v64, 0x3fb8aa3b, v64
	v_exp_f32_e32 v164, v64
	v_sub_f32_e32 v64, v91, v103
	v_mul_f32_e32 v64, 0x3fb8aa3b, v64
	v_exp_f32_e32 v166, v64
	v_sub_f32_e32 v64, v105, v103
	v_sub_f32_e32 v85, v102, v103
	v_mul_f32_e32 v64, 0x3fb8aa3b, v64
	v_mul_f32_e32 v85, 0x3fb8aa3b, v85
	v_exp_f32_e32 v168, v64
	v_sub_f32_e32 v64, v154, v103
	v_sub_f32_e32 v65, v155, v103
	v_mul_f32_e32 v64, 0x3fb8aa3b, v64
	v_exp_f32_e32 v170, v85
	v_mul_f32_e32 v65, 0x3fb8aa3b, v65
	v_exp_f32_e32 v172, v65
	v_exp_f32_e32 v174, v64
	v_mul_f32_e32 v64, v60, v170
	v_mul_f32_e32 v65, v61, v170
	v_mul_f32_e32 v66, v62, v170
	v_mul_f32_e32 v67, v63, v170
	v_cvt_pk_bf16_f32 v156, v166, v168
	v_accvgpr_write_b32 a0, v64
	v_accvgpr_write_b32 a1, v65
	v_accvgpr_write_b32 a2, v66
	v_accvgpr_write_b32 a3, v67
	v_mul_f32_e32 v64, v56, v170
	v_mul_f32_e32 v65, v57, v170
	v_cvt_pk_bf16_f32 v157, v174, v172
	v_mul_f32_e32 v66, v58, v170
	v_mul_f32_e32 v67, v59, v170
	v_accvgpr_read_b32 v85, a8
	v_accvgpr_write_b32 a4, v64
	v_accvgpr_read_b32 v91, a9
	v_cvt_pk_bf16_f32 v155, v162, v164
	v_accvgpr_write_b32 a5, v65
	v_accvgpr_write_b32 a6, v66
	v_accvgpr_write_b32 a7, v67
	v_accvgpr_read_b32 v163, a10


	v_max_f32_e32 v64, v85, v91


	v_accvgpr_read_b32 v171, a14
	v_max_f32_e32 v65, v163, v165


	v_max_f32_e32 v66, v171, v173
	v_max3_f32 v66, v167, v169, v66
	v_max3_f32 v105, v64, v65, v66
	ds_bpermute_b32 v90, v90, v105
	v_mul_f32_e32 v64, v52, v170
	v_mul_f32_e32 v65, v53, v170
	v_mul_f32_e32 v66, v54, v170
	v_mul_f32_e32 v67, v55, v170
	v_accvgpr_write_b32 a8, v64
	v_accvgpr_write_b32 a9, v65
	v_accvgpr_write_b32 a10, v66
	v_accvgpr_write_b32 a11, v67
	s_waitcnt lgkmcnt(0)

	v_max_f32_e32 v90, v105, v90
	ds_bpermute_b32 v105, v159, v90
	v_mul_f32_e32 v64, v48, v170
	v_mul_f32_e32 v65, v49, v170
	v_mul_f32_e32 v66, v50, v170
	v_mul_f32_e32 v67, v51, v170
	v_cvt_pk_bf16_f32 v154, v158, v160
	v_accvgpr_write_b32 a12, v64
	s_waitcnt lgkmcnt(0)
	v_max3_f32 v105, v104, v90, v105
	v_accvgpr_write_b32 a13, v65
	v_accvgpr_write_b32 a14, v66
	v_accvgpr_write_b32 a15, v67
	v_sub_f32_e32 v65, v85, v105
	v_mul_f32_e32 v65, 0x3fb8aa3b, v65
	v_sub_f32_e32 v67, v165, v105
	v_exp_f32_e32 v159, v65
	v_sub_f32_e32 v65, v91, v105
	v_mul_f32_e32 v67, 0x3fb8aa3b, v67
	v_mul_f32_e32 v65, 0x3fb8aa3b, v65
	v_exp_f32_e32 v165, v67
	v_sub_f32_e32 v67, v167, v105
	v_exp_f32_e32 v161, v65
	v_sub_f32_e32 v65, v163, v105
	v_mul_f32_e32 v67, 0x3fb8aa3b, v67
	v_mul_f32_e32 v65, 0x3fb8aa3b, v65
	v_exp_f32_e32 v167, v67
	v_sub_f32_e32 v67, v169, v105
	v_exp_f32_e32 v163, v65
	v_mul_f32_e32 v67, 0x3fb8aa3b, v67
	v_sub_f32_e32 v64, v104, v105
	v_exp_f32_e32 v169, v67
	v_sub_f32_e32 v67, v171, v105
	v_mul_f32_e32 v66, 0x3fb8aa3b, v64
	v_add_f32_e32 v64, 0, v158
	v_add_f32_e32 v65, 0, v159
	v_mul_f32_e32 v67, 0x3fb8aa3b, v67
	v_add_f32_e32 v64, v160, v64
	v_add_f32_e32 v65, v161, v65
	v_exp_f32_e32 v175, v67
	v_sub_f32_e32 v67, v173, v105
	v_add_f32_e32 v64, v162, v64
	v_add_f32_e32 v65, v163, v65
	v_mul_f32_e32 v67, 0x3fb8aa3b, v67
	v_exp_f32_e32 v173, v67
	v_exp_f32_e32 v171, v66
	v_add_f32_e32 v64, v164, v64
	v_add_f32_e32 v65, v165, v65
	v_bfe_u32 v164, v159, 16, 1
	v_add_f32_e32 v64, v166, v64
	v_add_f32_e32 v65, v167, v65
	v_mov_b32_e32 v158, v171
	v_add_f32_e32 v64, v168, v64
	v_add_f32_e32 v65, v169, v65
	v_mul_f32_e32 v66, v46, v158
	v_mul_f32_e32 v67, v47, v158
	v_add_f32_e32 v64, v174, v64
	v_add_f32_e32 v65, v175, v65
	v_mfma_f32_16x16x32_bf16 a[0:3], v[118:121], v[154:157], a[0:3]
	v_add_f32_e64 v64, v172, v64
	v_add_f32_e64 v65, v173, v65
	v_fma_f32 v90, v88, v170, v64
	v_fma_f32 v91, v89, v171, v65
	v_mul_f32_e32 v64, v44, v158
	v_mul_f32_e32 v65, v45, v158
	v_add3_u32 v159, v159, v164, s80
	v_accvgpr_write_b32 a16, v64
	v_accvgpr_write_b32 a17, v65
	v_accvgpr_write_b32 a18, v66
	v_accvgpr_write_b32 a19, v67
	v_mul_f32_e32 v64, v40, v158
	v_mul_f32_e32 v65, v41, v158
	v_mul_f32_e32 v66, v42, v158
	v_mul_f32_e32 v67, v43, v158
	v_mfma_f32_16x16x32_bf16 a[4:7], v[114:117], v[154:157], a[4:7]
	v_accvgpr_write_b32 a20, v64
	v_accvgpr_write_b32 a21, v65
	v_accvgpr_write_b32 a22, v66
	v_accvgpr_write_b32 a23, v67
	v_mul_f32_e32 v64, v36, v158
	v_mul_f32_e32 v65, v37, v158
	v_mul_f32_e32 v66, v38, v158
	v_mul_f32_e32 v67, v39, v158
	v_mfma_f32_16x16x32_bf16 a[8:11], v[110:113], v[154:157], a[8:11]
	v_accvgpr_write_b32 a24, v64
	v_bfe_u32 v162, v161, 16, 1
	v_mfma_f32_16x16x32_bf16 a[12:15], v[106:109], v[154:157], a[12:15]
	v_cvt_pk_bf16_f32 v156, v167, v169
	v_accvgpr_write_b32 a25, v65
	v_accvgpr_write_b32 a26, v66
	v_accvgpr_write_b32 a27, v67
	v_mul_f32_e32 v64, v32, v158
	v_mul_f32_e32 v65, v33, v158
	v_add3_u32 v161, v161, v162, s80
	v_mul_f32_e32 v66, v34, v158
	v_mul_f32_e32 v67, v35, v158
	v_cvt_pk_bf16_f32 v157, v175, v173
	v_accvgpr_write_b32 a28, v64
	v_cvt_pk_bf16_f32 v155, v163, v165
	v_perm_b32 v154, v161, v159, s4
	v_accvgpr_write_b32 a29, v65
	v_accvgpr_write_b32 a30, v66
	v_accvgpr_write_b32 a31, v67
	v_mfma_f32_16x16x32_bf16 a[16:19], v[118:121], v[154:157], a[16:19]
	v_mfma_f32_16x16x32_bf16 a[20:23], v[114:117], v[154:157], a[20:23]
	v_mfma_f32_16x16x32_bf16 a[24:27], v[110:113], v[154:157], a[24:27]
	v_mfma_f32_16x16x32_bf16 a[28:31], v[106:109], v[154:157], a[28:31]

.LBB0_436:
	s_nop 5
	v_accvgpr_read_b32 v105, a0
	v_accvgpr_read_b32 v91, a1
	v_accvgpr_read_b32 v90, a2
	v_accvgpr_read_b32 v85, a3


	v_accvgpr_read_b32 v65, a6
	v_accvgpr_read_b32 v64, a7
	v_max_f32_e32 v103, v105, v91


	v_max_f32_e32 v154, v90, v85

	v_max_f32_e32 v156, v65, v65
	v_accvgpr_read_b32 v67, a4
	v_accvgpr_read_b32 v66, a5
	v_max_f32_e32 v155, v156, v64
	v_max3_f32 v155, v67, v66, v155
	v_cmp_lt_i32_e32 vcc, v212, v210
	v_max3_f32 v103, v103, v154, v155
	s_mov_b32 s4, 0x7060302
	v_cndmask_b32_e32 v154, v209, v212, vcc
	v_lshlrev_b32_e32 v154, 2, v154
	ds_bpermute_b32 v154, v154, v103
	v_cmp_lt_i32_e32 vcc, v211, v210
	s_waitcnt lgkmcnt(0)
	v_max_f32_e32 v154, v154, v154
	v_max_f32_e32 v103, v103, v154
	v_cndmask_b32_e32 v154, v209, v211, vcc
	v_lshlrev_b32_e32 v154, 2, v154
	ds_bpermute_b32 v154, v154, v103
	s_waitcnt lgkmcnt(0)
	v_max3_f32 v103, v102, v103, v154
	v_sub_f32_e32 v105, v105, v103
	v_mul_f32_e32 v105, 0x3fb8aa3b, v105
	v_sub_f32_e32 v91, v91, v103
	v_exp_f32_e32 v105, v105
	v_mul_f32_e32 v91, 0x3fb8aa3b, v91
	v_sub_f32_e32 v90, v90, v103
	v_exp_f32_e32 v91, v91
	v_mul_f32_e32 v90, 0x3fb8aa3b, v90
	v_sub_f32_e32 v85, v85, v103
	v_exp_f32_e32 v90, v90
	v_mul_f32_e32 v85, 0x3fb8aa3b, v85
	v_sub_f32_e32 v67, v67, v103
	v_exp_f32_e32 v85, v85
	v_mul_f32_e32 v67, 0x3fb8aa3b, v67
	v_sub_f32_e32 v66, v66, v103
	v_add_f32_e32 v154, 0, v105
	v_exp_f32_e32 v67, v67
	v_mul_f32_e32 v66, 0x3fb8aa3b, v66
	v_sub_f32_e32 v65, v65, v103
	v_add_f32_e32 v154, v91, v154
	v_exp_f32_e32 v66, v66
	v_mul_f32_e32 v65, 0x3fb8aa3b, v65
	v_sub_f32_e32 v64, v64, v103
	v_sub_f32_e32 v102, v102, v103
	v_add_f32_e32 v154, v90, v154
	v_exp_f32_e32 v65, v65
	v_mul_f32_e32 v64, 0x3fb8aa3b, v64
	v_mul_f32_e32 v102, 0x3fb8aa3b, v102
	v_add_f32_e32 v154, v85, v154
	v_exp_f32_e32 v155, v64
	v_add_f32_e32 v154, v67, v154
	v_exp_f32_e32 v64, v102
	v_add_f32_e32 v154, v66, v154
	v_add_f32_e32 v154, v65, v154
	v_add_f32_e32 v154, v155, v154
	v_fmac_f32_e32 v154, v88, v64
	v_mul_f32_e32 v62, v62, v64
	v_mul_f32_e32 v63, v63, v64
	v_mul_f32_e32 v60, v60, v64
	v_mul_f32_e32 v61, v61, v64
	v_mul_f32_e32 v58, v58, v64
	v_mul_f32_e32 v59, v59, v64
	v_mul_f32_e32 v56, v56, v64
	v_mul_f32_e32 v57, v57, v64
	v_mul_f32_e32 v54, v54, v64
	v_mul_f32_e32 v55, v55, v64
	v_mul_f32_e32 v52, v52, v64
	v_mul_f32_e32 v53, v53, v64
	v_mul_f32_e32 v50, v50, v64
	v_mul_f32_e32 v51, v51, v64
	v_mul_f32_e32 v48, v48, v64
	v_mul_f32_e32 v49, v49, v64
	v_bfe_u32 v64, v155, 16, 1
	v_bfe_u32 v88, v65, 16, 1
	v_cvt_pk_bf16_f32 v66, v67, v66
	v_bfe_u32 v157, v85, 16, 1
	v_bfe_u32 v158, v90, 16, 1
	v_bfe_u32 v159, v91, 16, 1
	v_bfe_u32 v160, v105, 16, 1
	v_add3_u32 v105, v105, v160, s80
	v_add3_u32 v91, v91, v159, s80
	v_add3_u32 v90, v90, v158, s80
	v_add3_u32 v85, v85, v157, s80
	v_add3_u32 v65, v65, v88, s80
	v_add3_u32 v64, v155, v64, s80
	v_accvgpr_write_b32 a0, v60
	v_accvgpr_write_b32 a4, v56
	v_accvgpr_write_b32 a8, v52
	v_accvgpr_write_b32 a12, v48
	v_perm_b32 v67, v64, v65, s4
	v_perm_b32 v65, v85, v90, s4
	v_perm_b32 v64, v91, v105, s4
	v_accvgpr_write_b32 a1, v61
	v_accvgpr_write_b32 a2, v62
	v_accvgpr_write_b32 a3, v63
	v_accvgpr_write_b32 a5, v57
	v_accvgpr_write_b32 a6, v58
	v_accvgpr_write_b32 a7, v59
	v_accvgpr_write_b32 a9, v53
	v_accvgpr_write_b32 a10, v54
	v_accvgpr_write_b32 a11, v55
	v_accvgpr_write_b32 a13, v49
	v_accvgpr_write_b32 a14, v50
	v_accvgpr_write_b32 a15, v51
	v_mfma_f32_16x16x32_bf16 a[0:3], v[118:121], v[64:67], a[0:3]
	v_mov_b32_e32 v88, v154
	v_mfma_f32_16x16x32_bf16 a[4:7], v[114:117], v[64:67], a[4:7]
	v_mfma_f32_16x16x32_bf16 a[8:11], v[110:113], v[64:67], a[8:11]
	v_mfma_f32_16x16x32_bf16 a[12:15], v[106:109], v[64:67], a[12:15]
	s_add_i32 s4, s83, s71
	s_cmp_lt_u32 s4, s33
	s_cbranch_scc0 .LBB0_438
	s_branch .LBB0_457

.LBB0_456:
	s_nop 5
	v_accvgpr_read_b32 v55, a16
	v_accvgpr_read_b32 v54, a17
	v_accvgpr_read_b32 v53, a18
	v_accvgpr_read_b32 v52, a19


	v_accvgpr_read_b32 v49, a22
	v_accvgpr_read_b32 v48, a23
	v_max_f32_e32 v56, v55, v54


	v_max_f32_e32 v57, v53, v52


	v_accvgpr_read_b32 v51, a20
	v_accvgpr_read_b32 v50, a21
	v_max_f32_e32 v58, v49, v48
	v_max3_f32 v58, v51, v50, v58
	v_cmp_lt_i32_e32 vcc, v212, v210
	v_max3_f32 v56, v56, v57, v58
	s_mov_b32 s4, 0x7060302
	v_cndmask_b32_e32 v57, v209, v212, vcc
	v_lshlrev_b32_e32 v57, 2, v57
	ds_bpermute_b32 v57, v57, v56
	v_cmp_lt_i32_e32 vcc, v211, v210
	s_waitcnt lgkmcnt(0)
	v_max_f32_e32 v57, v57, v57
	v_max_f32_e32 v56, v56, v57
	v_cndmask_b32_e32 v57, v209, v211, vcc
	v_lshlrev_b32_e32 v57, 2, v57
	ds_bpermute_b32 v57, v57, v56
	s_waitcnt lgkmcnt(0)
	v_max3_f32 v56, v104, v56, v57
	v_sub_f32_e32 v55, v55, v56
	v_mul_f32_e32 v55, 0x3fb8aa3b, v55
	v_sub_f32_e32 v54, v54, v56
	v_exp_f32_e32 v55, v55
	v_mul_f32_e32 v54, 0x3fb8aa3b, v54
	v_sub_f32_e32 v53, v53, v56
	v_exp_f32_e32 v54, v54
	v_mul_f32_e32 v53, 0x3fb8aa3b, v53
	v_sub_f32_e32 v52, v52, v56
	v_exp_f32_e32 v53, v53
	v_mul_f32_e32 v52, 0x3fb8aa3b, v52
	v_sub_f32_e32 v51, v51, v56
	v_exp_f32_e32 v52, v52
	v_mul_f32_e32 v51, 0x3fb8aa3b, v51
	v_sub_f32_e32 v50, v50, v56
	v_add_f32_e32 v58, 0, v55
	v_exp_f32_e32 v51, v51
	v_mul_f32_e32 v50, 0x3fb8aa3b, v50
	v_sub_f32_e32 v49, v49, v56
	v_add_f32_e32 v58, v54, v58
	v_exp_f32_e32 v50, v50
	v_mul_f32_e32 v49, 0x3fb8aa3b, v49
	v_sub_f32_e32 v48, v48, v56
	v_sub_f32_e32 v57, v104, v56
	v_add_f32_e32 v58, v53, v58
	v_exp_f32_e32 v49, v49
	v_mul_f32_e32 v48, 0x3fb8aa3b, v48
	v_mul_f32_e32 v57, 0x3fb8aa3b, v57
	v_add_f32_e32 v58, v52, v58
	v_exp_f32_e32 v59, v48
	v_add_f32_e32 v58, v51, v58
	v_exp_f32_e32 v48, v57
	v_add_f32_e32 v58, v50, v58
	v_add_f32_e32 v58, v49, v58
	v_add_f32_e32 v58, v59, v58
	v_fmac_f32_e32 v58, v89, v48
	v_mul_f32_e32 v46, v46, v48
	v_mul_f32_e32 v47, v47, v48
	v_mul_f32_e32 v44, v44, v48
	v_mul_f32_e32 v45, v45, v48
	v_mul_f32_e32 v42, v42, v48
	v_mul_f32_e32 v43, v43, v48
	v_mul_f32_e32 v40, v40, v48
	v_mul_f32_e32 v41, v41, v48
	v_mul_f32_e32 v38, v38, v48
	v_mul_f32_e32 v39, v39, v48
	v_mul_f32_e32 v36, v36, v48
	v_mul_f32_e32 v37, v37, v48
	v_mul_f32_e32 v34, v34, v48
	v_mul_f32_e32 v35, v35, v48
	v_mul_f32_e32 v32, v32, v48
	v_mul_f32_e32 v33, v33, v48
	v_bfe_u32 v48, v59, 16, 1
	v_bfe_u32 v57, v49, 16, 1
	v_cvt_pk_bf16_f32 v50, v51, v50
	v_bfe_u32 v62, v52, 16, 1
	v_bfe_u32 v63, v53, 16, 1
	v_bfe_u32 v64, v54, 16, 1
	v_bfe_u32 v65, v55, 16, 1
	v_add3_u32 v55, v55, v65, s80
	v_add3_u32 v54, v54, v64, s80
	v_add3_u32 v53, v53, v63, s80
	v_add3_u32 v52, v52, v62, s80
	v_add3_u32 v49, v49, v57, s80
	v_add3_u32 v48, v59, v48, s80
	v_accvgpr_write_b32 a16, v44
	v_perm_b32 v51, v48, v49, s4
	v_perm_b32 v49, v52, v53, s4
	v_perm_b32 v48, v54, v55, s4
	v_accvgpr_write_b32 a17, v45
	v_accvgpr_write_b32 a18, v46
	v_accvgpr_write_b32 a19, v47
	v_mov_b32_e32 v89, v58
	v_mov_b32_e32 v104, v56
	v_mfma_f32_16x16x32_bf16 a[32:35], v[118:121], v[48:51], a[16:19]
	s_nop 2
	v_accvgpr_write_b32 a16, v40
	v_accvgpr_write_b32 a17, v41
	v_accvgpr_write_b32 a18, v42
	v_accvgpr_write_b32 a19, v43
	s_nop 1
	v_mfma_f32_16x16x32_bf16 a[36:39], v[114:117], v[48:51], a[16:19]
	s_nop 2
	v_accvgpr_write_b32 a16, v36
	v_accvgpr_write_b32 a17, v37
	v_accvgpr_write_b32 a18, v38
	v_accvgpr_write_b32 a19, v39
	s_nop 1
	v_mfma_f32_16x16x32_bf16 a[40:43], v[110:113], v[48:51], a[16:19]
	s_nop 2
	v_accvgpr_write_b32 a16, v32
	v_accvgpr_write_b32 a17, v33
	v_accvgpr_write_b32 a18, v34
	v_accvgpr_write_b32 a19, v35
	s_nop 1
	v_mfma_f32_16x16x32_bf16 a[44:47], v[106:109], v[48:51], a[16:19]

.LBB0_463:
	s_add_u32 s29, s90, vcc_lo
	s_addc_u32 s77, s91, vcc_hi
	s_lshl_b64 s[4:5], s[6:7], s4
	s_add_u32 s4, s29, s4
	s_addc_u32 s5, s77, s5
	v_lshl_add_u64 v[66:67], v[66:67], 0, v[68:69]
	s_movk_i32 s29, 0x300
	v_lshl_add_u64 v[64:65], v[64:65], 1, s[4:5]
	v_mad_u64_u32 v[88:89], s[4:5], v66, s29, v[86:87]
	v_mov_b32_e32 v66, v89
	v_mad_u64_u32 v[66:67], s[4:5], v67, s29, v[66:67]
	v_mov_b32_e32 v89, v66
	global_load_dwordx4 v[146:149], v[88:89], off
	global_load_dwordx4 v[142:145], v[88:89], off offset:64
	v_add_co_u32_e32 v88, vcc, s93, v88
	v_mov_b32_e32 v85, v193
	s_nop 0
	v_addc_co_u32_e32 v89, vcc, 0, v66, vcc
	v_mul_u32_u24_e32 v66, s28, v68
	v_lshlrev_b32_e32 v192, 1, v66
	v_lshl_add_u64 v[64:65], v[64:65], 0, v[192:193]
	v_lshl_add_u64 v[64:65], v[64:65], 0, v[84:85]
	s_lshl_b32 s78, s28, 5
	v_lshl_add_u64 v[66:67], v[64:65], 0, s[78:79]
	global_load_dwordx4 v[150:153], v[88:89], off
	global_load_dwordx4 v[138:141], v[88:89], off offset:64
	global_load_dwordx2 v[118:119], v[64:65], off
	global_load_dwordx2 v[120:121], v[64:65], off offset:32
	global_load_dwordx2 v[114:115], v[66:67], off
	global_load_dwordx2 v[116:117], v[66:67], off offset:32
	v_lshl_add_u64 v[64:65], v[66:67], 0, s[78:79]
	v_lshl_add_u64 v[66:67], v[64:65], 0, s[78:79]
	global_load_dwordx2 v[110:111], v[64:65], off
	global_load_dwordx2 v[112:113], v[64:65], off offset:32
	global_load_dwordx2 v[106:107], v[66:67], off
	global_load_dwordx2 v[108:109], v[66:67], off offset:32
	s_cmp_ge_i32 s31, s76
	s_cbranch_scc1 .LBB0_487
	s_mov_b64 s[28:29], -1
	s_and_b64 vcc, exec, s[26:27]
	s_cbranch_vccz .LBB0_466
	s_waitcnt vmcnt(23)
	v_mfma_f32_16x16x32_bf16 a[32:35], v[16:19], v[0:3], 0
	v_cmp_lt_i32_e32 vcc, v212, v210
	s_mov_b32 s4, 0x7060302
	s_mov_b64 s[28:29], 0
	s_waitcnt vmcnt(22)
	v_mfma_f32_16x16x32_bf16 a[32:35], v[20:23], v[4:7], a[32:35]
	v_mfma_f32_16x16x32_bf16 a[40:43], v[16:19], v[8:11], 0
	s_waitcnt vmcnt(21)
	v_mfma_f32_16x16x32_bf16 a[44:47], v[28:31], v[8:11], 0
	s_nop 4
	s_nop 3
	v_accvgpr_read_b32 v64, a32
	v_accvgpr_read_b32 v65, a33
	v_accvgpr_read_b32 v66, a34
	v_accvgpr_read_b32 v67, a35
	v_mfma_f32_16x16x32_bf16 a[32:35], v[28:31], v[0:3], 0


	v_max_f32_e32 v85, v64, v65
	s_waitcnt vmcnt(20)
	v_mfma_f32_16x16x32_bf16 a[32:35], v[24:27], v[4:7], a[32:35]


	v_max_f32_e32 v88, v66, v67
	v_mfma_f32_16x16x32_bf16 a[40:43], v[20:23], v[12:15], a[40:43]
	v_mfma_f32_16x16x32_bf16 a[44:47], v[24:27], v[12:15], a[44:47]
	s_nop 2
	s_nop 3
	v_accvgpr_read_b32 v154, a34
	v_accvgpr_read_b32 v155, a35


	v_accvgpr_read_b32 v89, a32
	v_accvgpr_read_b32 v104, a33
	v_max_f32_e32 v102, v154, v155
	v_max3_f32 v102, v89, v104, v102
	v_max3_f32 v85, v85, v88, v102
	v_cndmask_b32_e32 v88, v209, v212, vcc
	v_lshlrev_b32_e32 v159, 2, v88
	ds_bpermute_b32 v88, v159, v85
	v_cmp_lt_i32_e32 vcc, v211, v210
	v_accvgpr_read_b32 v167, a43
	v_accvgpr_read_b32 v173, a46
	v_accvgpr_read_b32 v174, a47
	s_waitcnt lgkmcnt(0)
	v_max_f32_e32 v88, v88, v88
	v_max_f32_e32 v85, v85, v88
	v_cndmask_b32_e32 v88, v209, v211, vcc
	v_lshlrev_b32_e32 v161, 2, v88
	ds_bpermute_b32 v88, v161, v85
	v_accvgpr_read_b32 v171, a45
	s_waitcnt lgkmcnt(0)
	v_max3_f32 v102, v103, v85, v88
	v_sub_f32_e32 v64, v64, v102
	v_mul_f32_e32 v64, 0x3fb8aa3b, v64
	v_exp_f32_e32 v88, v64
	v_sub_f32_e32 v64, v65, v102
	v_mul_f32_e32 v64, 0x3fb8aa3b, v64
	v_exp_f32_e32 v158, v64
	v_sub_f32_e32 v64, v66, v102
	v_mul_f32_e32 v64, 0x3fb8aa3b, v64
	v_exp_f32_e32 v160, v64
	v_sub_f32_e32 v64, v67, v102
	v_mul_f32_e32 v64, 0x3fb8aa3b, v64
	v_exp_f32_e32 v162, v64
	v_sub_f32_e32 v64, v89, v102
	v_mul_f32_e32 v64, 0x3fb8aa3b, v64
	v_exp_f32_e32 v164, v64
	v_sub_f32_e32 v64, v104, v102
	v_sub_f32_e32 v85, v103, v102
	v_mul_f32_e32 v64, 0x3fb8aa3b, v64
	v_mul_f32_e32 v85, 0x3fb8aa3b, v85
	v_exp_f32_e32 v166, v64
	v_sub_f32_e32 v64, v154, v102
	v_sub_f32_e32 v65, v155, v102
	v_mul_f32_e32 v64, 0x3fb8aa3b, v64
	v_exp_f32_e32 v168, v85
	v_mul_f32_e32 v65, 0x3fb8aa3b, v65
	v_exp_f32_e32 v170, v65
	v_exp_f32_e32 v172, v64
	v_mul_f32_e32 v64, v60, v168
	v_mul_f32_e32 v65, v61, v168
	v_mul_f32_e32 v66, v62, v168
	v_mul_f32_e32 v67, v63, v168
	v_cvt_pk_bf16_f32 v154, v88, v158
	v_accvgpr_write_b32 a32, v64
	v_accvgpr_write_b32 a33, v65
	v_accvgpr_write_b32 a34, v66
	v_accvgpr_write_b32 a35, v67
	v_mul_f32_e32 v64, v56, v168
	v_mul_f32_e32 v65, v57, v168
	v_cvt_pk_bf16_f32 v157, v172, v170
	v_mul_f32_e32 v66, v58, v168
	v_mul_f32_e32 v67, v59, v168
	v_accvgpr_read_b32 v85, a40
	v_accvgpr_write_b32 a36, v64
	v_accvgpr_read_b32 v163, a41
	v_cvt_pk_bf16_f32 v155, v160, v162
	v_accvgpr_write_b32 a37, v65
	v_accvgpr_write_b32 a38, v66
	v_accvgpr_write_b32 a39, v67
	v_accvgpr_read_b32 v165, a42


	v_max_f32_e32 v64, v85, v163


	v_max_f32_e32 v65, v165, v167


	v_cvt_pk_bf16_f32 v156, v164, v166
	v_accvgpr_read_b32 v169, a44
	v_max_f32_e32 v66, v173, v174
	v_max3_f32 v66, v169, v171, v66
	v_max3_f32 v89, v64, v65, v66
	ds_bpermute_b32 v104, v159, v89
	v_mul_f32_e32 v64, v52, v168
	v_mul_f32_e32 v65, v53, v168
	v_mul_f32_e32 v66, v54, v168
	v_mul_f32_e32 v67, v55, v168
	s_waitcnt vmcnt(18)
	v_mfma_f32_16x16x32_bf16 a[32:35], v[134:137], v[154:157], a[32:35]
	v_accvgpr_write_b32 a40, v64
	v_accvgpr_write_b32 a41, v65
	v_accvgpr_write_b32 a42, v66
	v_accvgpr_write_b32 a43, v67
	s_waitcnt lgkmcnt(0)

	v_max_f32_e32 v89, v89, v104
	ds_bpermute_b32 v104, v161, v89
	v_mul_f32_e32 v64, v48, v168
	v_mul_f32_e32 v65, v49, v168
	v_mul_f32_e32 v66, v50, v168
	v_mul_f32_e32 v67, v51, v168
	s_waitcnt vmcnt(16)
	v_mfma_f32_16x16x32_bf16 a[36:39], v[130:133], v[154:157], a[36:39]
	v_accvgpr_write_b32 a44, v64
	s_waitcnt lgkmcnt(0)
	v_max3_f32 v104, v105, v89, v104
	v_accvgpr_write_b32 a45, v65
	v_accvgpr_write_b32 a46, v66
	v_accvgpr_write_b32 a47, v67
	v_sub_f32_e32 v65, v85, v104
	v_mul_f32_e32 v65, 0x3fb8aa3b, v65
	v_exp_f32_e32 v89, v65
	v_sub_f32_e32 v65, v163, v104
	v_mul_f32_e32 v65, 0x3fb8aa3b, v65
	v_exp_f32_e32 v159, v65
	v_sub_f32_e32 v65, v165, v104
	v_mul_f32_e32 v65, 0x3fb8aa3b, v65
	v_exp_f32_e32 v161, v65
	v_sub_f32_e32 v65, v167, v104
	v_mul_f32_e32 v65, 0x3fb8aa3b, v65
	v_exp_f32_e32 v163, v65
	v_sub_f32_e32 v65, v169, v104
	v_mul_f32_e32 v65, 0x3fb8aa3b, v65
	v_exp_f32_e32 v165, v65
	v_sub_f32_e32 v65, v171, v104
	v_mul_f32_e32 v65, 0x3fb8aa3b, v65
	v_exp_f32_e32 v167, v65
	v_sub_f32_e32 v65, v173, v104
	v_sub_f32_e32 v64, v105, v104
	v_mul_f32_e32 v65, 0x3fb8aa3b, v65
	v_mul_f32_e32 v64, 0x3fb8aa3b, v64
	v_exp_f32_e32 v173, v65
	v_sub_f32_e32 v65, v174, v104
	v_mul_f32_e32 v65, 0x3fb8aa3b, v65
	v_exp_f32_e32 v169, v64
	v_exp_f32_e32 v171, v65
	s_waitcnt vmcnt(14)
	v_mfma_f32_16x16x32_bf16 a[40:43], v[126:129], v[154:157], a[40:43]
	v_add_f32_e64 v64, v88, 0
	v_add_f32_e64 v65, v89, 0
	v_mov_b32_e32 v66, v169
	v_add_f32_e32 v64, v158, v64
	v_add_f32_e32 v65, v159, v65
	s_waitcnt vmcnt(12)
	v_mfma_f32_16x16x32_bf16 a[44:47], v[122:125], v[154:157], a[44:47]
	v_mul_f32_e64 v156, v46, v66
	v_mul_f32_e64 v157, v47, v66
	v_mul_f32_e32 v154, v44, v66
	v_mul_f32_e32 v155, v45, v66
	v_bfe_u32 v67, v171, 16, 1
	v_add3_u32 v67, v171, v67, s80
	v_accvgpr_write_b32 a48, v154
	v_accvgpr_write_b32 a49, v155
	v_accvgpr_write_b32 a50, v156
	v_accvgpr_write_b32 a51, v157
	v_mul_f32_e32 v154, v40, v66
	v_mul_f32_e32 v155, v41, v66
	v_add_f32_e32 v64, v160, v64
	v_add_f32_e32 v65, v161, v65
	v_mul_f32_e32 v156, v42, v66
	v_mul_f32_e32 v157, v43, v66
	v_add_f32_e32 v64, v162, v64
	v_add_f32_e32 v65, v163, v65
	v_accvgpr_write_b32 a52, v154
	v_accvgpr_write_b32 a53, v155
	v_accvgpr_write_b32 a54, v156
	v_accvgpr_write_b32 a55, v157
	v_mul_f32_e32 v154, v36, v66
	v_mul_f32_e32 v155, v37, v66
	v_add_f32_e32 v64, v164, v64
	v_add_f32_e32 v65, v165, v65
	v_mul_f32_e32 v156, v38, v66
	v_mul_f32_e32 v157, v39, v66
	v_add_f32_e32 v64, v166, v64
	v_add_f32_e32 v65, v167, v65
	v_accvgpr_write_b32 a56, v154
	v_bfe_u32 v85, v173, 16, 1
	v_bfe_u32 v160, v163, 16, 1
	v_bfe_u32 v162, v161, 16, 1
	v_bfe_u32 v164, v159, 16, 1
	v_bfe_u32 v166, v89, 16, 1
	v_accvgpr_write_b32 a57, v155
	v_accvgpr_write_b32 a58, v156
	v_accvgpr_write_b32 a59, v157
	v_mul_f32_e32 v154, v32, v66
	v_mul_f32_e32 v155, v33, v66
	v_add_f32_e32 v64, v172, v64
	v_add_f32_e32 v65, v173, v65
	v_add3_u32 v89, v89, v166, s80
	v_add3_u32 v164, v159, v164, s80
	v_add3_u32 v159, v161, v162, s80
	v_add3_u32 v162, v163, v160, s80
	v_add3_u32 v85, v173, v85, s80
	v_mul_f32_e32 v156, v34, v66
	v_mul_f32_e32 v157, v35, v66
	v_add_f32_e32 v64, v170, v64
	v_add_f32_e32 v65, v171, v65
	v_accvgpr_write_b32 a60, v154
	v_perm_b32 v161, v67, v85, s4
	v_cvt_pk_bf16_f32 v160, v165, v167
	v_perm_b32 v159, v162, v159, s4
	v_perm_b32 v158, v164, v89, s4
	v_accvgpr_write_b32 a61, v155
	v_accvgpr_write_b32 a62, v156
	v_accvgpr_write_b32 a63, v157
	v_fma_f32 v64, v90, v168, v64
	v_fma_f32 v65, v91, v169, v65
	v_mfma_f32_16x16x32_bf16 a[48:51], v[134:137], v[158:161], a[48:51]
	v_mfma_f32_16x16x32_bf16 a[52:55], v[130:133], v[158:161], a[52:55]
	v_mfma_f32_16x16x32_bf16 a[56:59], v[126:129], v[158:161], a[56:59]
	v_mfma_f32_16x16x32_bf16 a[60:63], v[122:125], v[158:161], a[60:63]

.LBB0_486:
	s_nop 4
	v_accvgpr_read_b32 v104, a0
	v_accvgpr_read_b32 v89, a1
	v_accvgpr_read_b32 v88, a2
	v_accvgpr_read_b32 v85, a3


	v_accvgpr_read_b32 v65, a6
	v_accvgpr_read_b32 v64, a7
	v_max_f32_e32 v102, v104, v89


	v_max_f32_e32 v154, v88, v85

	v_max_f32_e32 v156, v65, v65
	v_accvgpr_read_b32 v67, a4
	v_accvgpr_read_b32 v66, a5
	v_max_f32_e32 v155, v156, v64
	v_max3_f32 v155, v67, v66, v155
	v_cmp_lt_i32_e32 vcc, v212, v210
	v_max3_f32 v102, v102, v154, v155
	s_mov_b32 s4, 0x7060302
	v_cndmask_b32_e32 v154, v209, v212, vcc
	v_lshlrev_b32_e32 v154, 2, v154
	ds_bpermute_b32 v154, v154, v102
	v_cmp_lt_i32_e32 vcc, v211, v210
	s_waitcnt lgkmcnt(0)
	v_max_f32_e32 v154, v154, v154
	v_max_f32_e32 v102, v102, v154
	v_cndmask_b32_e32 v154, v209, v211, vcc
	v_lshlrev_b32_e32 v154, 2, v154
	ds_bpermute_b32 v154, v154, v102
	s_waitcnt lgkmcnt(0)
	v_max3_f32 v102, v103, v102, v154
	v_sub_f32_e32 v104, v104, v102
	v_mul_f32_e32 v104, 0x3fb8aa3b, v104
	v_sub_f32_e32 v89, v89, v102
	v_exp_f32_e32 v104, v104
	v_mul_f32_e32 v89, 0x3fb8aa3b, v89
	v_sub_f32_e32 v88, v88, v102
	v_exp_f32_e32 v89, v89
	v_mul_f32_e32 v88, 0x3fb8aa3b, v88
	v_sub_f32_e32 v85, v85, v102
	v_exp_f32_e32 v88, v88
	v_mul_f32_e32 v85, 0x3fb8aa3b, v85
	v_sub_f32_e32 v67, v67, v102
	v_exp_f32_e32 v85, v85
	v_mul_f32_e32 v67, 0x3fb8aa3b, v67
	v_sub_f32_e32 v66, v66, v102
	v_add_f32_e32 v154, 0, v104
	v_exp_f32_e32 v67, v67
	v_mul_f32_e32 v66, 0x3fb8aa3b, v66
	v_sub_f32_e32 v65, v65, v102
	v_add_f32_e32 v154, v89, v154
	v_exp_f32_e32 v66, v66
	v_mul_f32_e32 v65, 0x3fb8aa3b, v65
	v_sub_f32_e32 v64, v64, v102
	v_sub_f32_e32 v103, v103, v102
	v_add_f32_e32 v154, v88, v154
	v_exp_f32_e32 v65, v65
	v_mul_f32_e32 v64, 0x3fb8aa3b, v64
	v_mul_f32_e32 v103, 0x3fb8aa3b, v103
	v_add_f32_e32 v154, v85, v154
	v_exp_f32_e32 v155, v64
	v_add_f32_e32 v154, v67, v154
	v_exp_f32_e32 v64, v103
	v_add_f32_e32 v154, v66, v154
	v_add_f32_e32 v154, v65, v154
	v_add_f32_e32 v154, v155, v154
	v_fmac_f32_e32 v154, v90, v64
	v_mul_f32_e32 v62, v62, v64
	v_mul_f32_e32 v63, v63, v64
	v_mul_f32_e32 v60, v60, v64
	v_mul_f32_e32 v61, v61, v64
	v_mul_f32_e32 v58, v58, v64
	v_mul_f32_e32 v59, v59, v64
	v_mul_f32_e32 v56, v56, v64
	v_mul_f32_e32 v57, v57, v64
	v_mul_f32_e32 v54, v54, v64
	v_mul_f32_e32 v55, v55, v64
	v_mul_f32_e32 v52, v52, v64
	v_mul_f32_e32 v53, v53, v64
	v_mul_f32_e32 v50, v50, v64
	v_mul_f32_e32 v51, v51, v64
	v_mul_f32_e32 v48, v48, v64
	v_mul_f32_e32 v49, v49, v64
	v_bfe_u32 v64, v155, 16, 1
	v_bfe_u32 v90, v65, 16, 1
	v_cvt_pk_bf16_f32 v66, v67, v66
	v_bfe_u32 v157, v85, 16, 1
	v_bfe_u32 v158, v88, 16, 1
	v_bfe_u32 v159, v89, 16, 1
	v_bfe_u32 v160, v104, 16, 1
	v_add3_u32 v104, v104, v160, s80
	v_add3_u32 v89, v89, v159, s80
	v_add3_u32 v88, v88, v158, s80
	v_add3_u32 v85, v85, v157, s80
	v_add3_u32 v65, v65, v90, s80
	v_add3_u32 v64, v155, v64, s80
	v_accvgpr_write_b32 a0, v60
	v_perm_b32 v67, v64, v65, s4
	v_perm_b32 v65, v85, v88, s4
	v_perm_b32 v64, v89, v104, s4
	v_accvgpr_write_b32 a1, v61
	v_accvgpr_write_b32 a2, v62
	v_accvgpr_write_b32 a3, v63
	v_mov_b32_e32 v90, v154
	s_waitcnt vmcnt(18)
	v_mfma_f32_16x16x32_bf16 a[32:35], v[134:137], v[64:67], a[0:3]
	s_nop 2
	v_accvgpr_write_b32 a0, v56
	v_accvgpr_write_b32 a1, v57
	v_accvgpr_write_b32 a2, v58
	v_accvgpr_write_b32 a3, v59
	s_waitcnt vmcnt(16)
	s_nop 0
	v_mfma_f32_16x16x32_bf16 a[36:39], v[130:133], v[64:67], a[0:3]
	s_nop 2
	v_accvgpr_write_b32 a0, v52
	v_accvgpr_write_b32 a1, v53
	v_accvgpr_write_b32 a2, v54
	v_accvgpr_write_b32 a3, v55
	s_waitcnt vmcnt(14)
	s_nop 0
	v_mfma_f32_16x16x32_bf16 a[40:43], v[126:129], v[64:67], a[0:3]
	s_nop 2
	v_accvgpr_write_b32 a0, v48
	v_accvgpr_write_b32 a1, v49
	v_accvgpr_write_b32 a2, v50
	v_accvgpr_write_b32 a3, v51
	s_waitcnt vmcnt(12)
	s_nop 0
	v_mfma_f32_16x16x32_bf16 a[44:47], v[122:125], v[64:67], a[0:3]
	s_add_i32 s4, s83, s71
	s_add_i32 s4, s4, 1
	s_cmp_lt_u32 s4, s33
	s_cbranch_scc0 .LBB0_489
	s_branch .LBB0_508

.LBB0_507:
	s_nop 4
	v_accvgpr_read_b32 v23, a0
	v_accvgpr_read_b32 v22, a1
	v_accvgpr_read_b32 v21, a2
	v_accvgpr_read_b32 v20, a3


	v_accvgpr_read_b32 v17, a6
	v_accvgpr_read_b32 v16, a7
	v_max_f32_e32 v24, v23, v22


	v_max_f32_e32 v25, v21, v20


	v_accvgpr_read_b32 v19, a4
	v_accvgpr_read_b32 v18, a5
	v_max_f32_e32 v26, v17, v16
	v_max3_f32 v26, v19, v18, v26
	v_cmp_lt_i32_e32 vcc, v212, v210
	v_max3_f32 v24, v24, v25, v26
	s_mov_b32 s4, 0x7060302
	v_cndmask_b32_e32 v25, v209, v212, vcc
	v_lshlrev_b32_e32 v25, 2, v25
	ds_bpermute_b32 v25, v25, v24
	v_cmp_lt_i32_e32 vcc, v211, v210
	s_waitcnt lgkmcnt(0)
	v_max_f32_e32 v25, v25, v25
	v_max_f32_e32 v24, v24, v25
	v_cndmask_b32_e32 v25, v209, v211, vcc
	v_lshlrev_b32_e32 v25, 2, v25
	ds_bpermute_b32 v25, v25, v24
	s_waitcnt lgkmcnt(0)
	v_max3_f32 v48, v105, v24, v25
	v_sub_f32_e32 v23, v23, v48
	v_mul_f32_e32 v23, 0x3fb8aa3b, v23
	v_sub_f32_e32 v22, v22, v48
	v_exp_f32_e32 v49, v23
	v_mul_f32_e32 v22, 0x3fb8aa3b, v22
	v_sub_f32_e32 v21, v21, v48
	v_exp_f32_e32 v50, v22
	v_mul_f32_e32 v21, 0x3fb8aa3b, v21
	v_sub_f32_e32 v20, v20, v48
	v_exp_f32_e32 v51, v21
	v_mul_f32_e32 v20, 0x3fb8aa3b, v20
	v_sub_f32_e32 v19, v19, v48
	v_exp_f32_e32 v52, v20
	v_mul_f32_e32 v19, 0x3fb8aa3b, v19
	v_sub_f32_e32 v18, v18, v48
	v_add_f32_e32 v23, 0, v49
	v_exp_f32_e32 v53, v19
	v_mul_f32_e32 v18, 0x3fb8aa3b, v18
	v_sub_f32_e32 v17, v17, v48
	v_add_f32_e32 v22, v50, v23
	v_exp_f32_e32 v54, v18
	v_mul_f32_e32 v17, 0x3fb8aa3b, v17
	v_sub_f32_e32 v16, v16, v48
	v_sub_f32_e32 v24, v105, v48
	v_add_f32_e32 v21, v51, v22
	v_exp_f32_e32 v55, v17
	v_mul_f32_e32 v16, 0x3fb8aa3b, v16
	v_mul_f32_e32 v24, 0x3fb8aa3b, v24
	v_add_f32_e32 v20, v52, v21
	v_exp_f32_e32 v56, v16
	v_add_f32_e32 v19, v53, v20
	v_exp_f32_e32 v28, v24
	v_add_f32_e32 v18, v54, v19
	v_add_f32_e32 v17, v55, v18
	v_add_f32_e32 v57, v56, v17
	v_fmac_f32_e32 v57, v91, v28
	v_mul_f32_e32 v18, v46, v28
	v_mul_f32_e32 v19, v47, v28
	v_mul_f32_e32 v16, v44, v28
	v_mul_f32_e32 v17, v45, v28
	v_mul_f32_e32 v22, v42, v28
	v_mul_f32_e32 v23, v43, v28
	v_mul_f32_e32 v20, v40, v28
	v_mul_f32_e32 v21, v41, v28
	v_mul_f32_e32 v26, v38, v28
	v_mul_f32_e32 v27, v39, v28
	v_mul_f32_e32 v24, v36, v28
	v_mul_f32_e32 v25, v37, v28
	v_mul_f32_e32 v30, v34, v28
	v_mul_f32_e32 v31, v35, v28
	v_mul_f32_e32 v29, v33, v28
	v_mul_f32_e32 v28, v32, v28
	v_cvt_pk_bf16_f32 v34, v53, v54
	v_accvgpr_write_b32 a0, v16
	v_cvt_pk_bf16_f32 v35, v55, v56
	v_cvt_pk_bf16_f32 v33, v51, v52
	v_cvt_pk_bf16_f32 v32, v49, v50
	v_accvgpr_write_b32 a1, v17
	v_accvgpr_write_b32 a2, v18
	v_accvgpr_write_b32 a3, v19
	v_mov_b32_e32 v91, v57
	v_mov_b32_e32 v105, v48
	s_waitcnt vmcnt(18)
	v_mfma_f32_16x16x32_bf16 a[16:19], v[134:137], v[32:35], a[0:3]
	s_nop 2
	v_accvgpr_write_b32 a0, v20
	v_accvgpr_write_b32 a1, v21
	v_accvgpr_write_b32 a2, v22
	v_accvgpr_write_b32 a3, v23
	s_waitcnt vmcnt(16)
	s_nop 0
	v_mfma_f32_16x16x32_bf16 a[20:23], v[130:133], v[32:35], a[0:3]
	s_nop 2
	v_accvgpr_write_b32 a0, v24
	v_accvgpr_write_b32 a1, v25
	v_accvgpr_write_b32 a2, v26
	v_accvgpr_write_b32 a3, v27
	s_waitcnt vmcnt(14)
	s_nop 0
	v_mfma_f32_16x16x32_bf16 a[24:27], v[126:129], v[32:35], a[0:3]
	s_nop 2
	v_accvgpr_write_b32 a0, v28
	v_accvgpr_write_b32 a1, v29
	v_accvgpr_write_b32 a2, v30
	v_accvgpr_write_b32 a3, v31
	s_waitcnt vmcnt(12)
	s_nop 0
	v_mfma_f32_16x16x32_bf16 a[28:31], v[122:125], v[32:35], a[0:3]
